# combo17 + write-through (sc1) stores in P0 transposes and P1 rows: the grid barrier's L2 write-back has nothing left to flush
# baseline (speedup 1.0000x reference)
.LBB0_29:
	v_add_u32_e32 v0, s4, v18
	v_mov_b32_e32 v21, v1
	v_mov_b32_e32 v23, v1
	v_mov_b32_e32 v25, v1
	v_mov_b32_e32 v27, v1
	v_add_u32_e32 v20, 0x2000, v0
	v_add_u32_e32 v22, 0x4000, v0
	v_add_u32_e32 v24, 0x6000, v0
	v_add_u32_e32 v26, 0x8000, v0
	v_mov_b32_e32 v29, v1
	v_mov_b32_e32 v31, v1
	v_lshl_add_u64 v[50:51], v[0:1], 2, v[16:17]
	v_add_u32_e32 v28, 0xa000, v0
	v_add_u32_e32 v30, 0xc000, v0
	v_add_u32_e32 v0, 0xe000, v0
	v_lshl_add_u64 v[20:21], v[20:21], 2, v[16:17]
	v_lshl_add_u64 v[22:23], v[22:23], 2, v[16:17]
	v_lshl_add_u64 v[24:25], v[24:25], 2, v[16:17]
	v_lshl_add_u64 v[26:27], v[26:27], 2, v[16:17]
	v_lshl_add_u64 v[28:29], v[28:29], 2, v[16:17]
	v_lshl_add_u64 v[30:31], v[30:31], 2, v[16:17]
	v_lshl_add_u64 v[52:53], v[0:1], 2, v[16:17]
	global_load_dword v0, v[50:51], off nt
	s_nop 0
	global_load_dword v20, v[20:21], off nt
	s_nop 0
	global_load_dword v21, v[22:23], off nt
	s_nop 0
	global_load_dword v22, v[24:25], off nt
	global_load_dword v23, v[26:27], off nt
	s_nop 0
	global_load_dword v24, v[28:29], off nt
	global_load_dword v25, v[30:31], off nt
	global_load_dword v26, v[52:53], off nt
	s_add_i32 s4, s4, 0x10000
	v_add_u32_e32 v27, 0x400, v19
	s_cmp_lg_u32 s4, 0x40000
	s_waitcnt vmcnt(6)
	ds_write2_b32 v19, v0, v20 offset1:66
	s_waitcnt vmcnt(4)
	ds_write2_b32 v19, v21, v22 offset0:132 offset1:198
	s_waitcnt vmcnt(2)
	ds_write2_b32 v27, v23, v24 offset0:8 offset1:74
	s_waitcnt vmcnt(0)
	ds_write2_b32 v27, v25, v26 offset0:140 offset1:206
	v_add_u32_e32 v19, 0x840, v19
	s_cbranch_scc1 .LBB0_29
	s_waitcnt lgkmcnt(0)
	ds_read2_b32 v[16:17], v34 offset1:8
	ds_read2_b32 v[18:19], v34 offset0:33 offset1:41
	ds_read2_b32 v[20:21], v34 offset0:66 offset1:74
	ds_read2_b32 v[22:23], v34 offset0:99 offset1:107
	v_mov_b32_e32 v26, v1
	s_waitcnt lgkmcnt(3)
	v_mul_f32_e32 v0, 0x43800000, v16
	s_waitcnt lgkmcnt(2)
	v_mul_f32_e32 v16, 0x43800000, v18
	v_med3_f32 v0, v0, s15, v48
	v_med3_f32 v16, v16, s15, v48
	v_cvt_pk_fp8_f32 v26, v0, v16
	ds_read2_b32 v[28:29], v34 offset0:132 offset1:140
	ds_read2_b32 v[30:31], v34 offset0:165 offset1:173
	ds_read2_b32 v[50:51], v34 offset0:198 offset1:206
	s_waitcnt lgkmcnt(4)
	v_mul_f32_e32 v18, 0x43800000, v20
	s_waitcnt lgkmcnt(3)
	v_mul_f32_e32 v20, 0x43800000, v22
	v_med3_f32 v0, v18, s15, v48
	v_med3_f32 v16, v20, s15, v48
	ds_read2_b32 v[52:53], v34 offset0:231 offset1:239
	v_cvt_pk_fp8_f32 v26, v0, v16 op_sel:[0,0,1]
	s_waitcnt lgkmcnt(3)
	v_mul_f32_e32 v0, 0x43800000, v28
	s_waitcnt lgkmcnt(2)
	v_mul_f32_e32 v16, 0x43800000, v30
	v_med3_f32 v0, v0, s15, v48
	v_med3_f32 v16, v16, s15, v48
	v_mov_b32_e32 v27, v1
	v_cvt_pk_fp8_f32 v27, v0, v16
	s_add_i32 s4, s22, 0xffff8000
	s_waitcnt lgkmcnt(1)
	v_mul_f32_e32 v18, 0x43800000, v50
	s_waitcnt lgkmcnt(0)
	v_mul_f32_e32 v0, 0x43800000, v52
	s_lshr_b32 s4, s4, 1
	v_med3_f32 v16, v18, s15, v48
	v_med3_f32 v0, v0, s15, v48
	s_and_b32 s4, s4, 0x7fffffc0
	v_cvt_pk_fp8_f32 v27, v16, v0 op_sel:[0,0,1]
	v_or_b32_e32 v0, s6, v33
	v_lshl_add_u64 v[24:25], v[8:9], 0, s[4:5]
	v_lshlrev_b32_e32 v0, 12, v0
	v_lshl_add_u64 v[54:55], v[24:25], 0, v[0:1]
	v_mul_f32_e32 v0, 0x43800000, v17
	v_mul_f32_e32 v16, 0x43800000, v19
	v_med3_f32 v0, v0, s15, v48
	v_med3_f32 v18, v16, s15, v48
	v_mov_b32_e32 v16, v1
	v_cvt_pk_fp8_f32 v16, v0, v18
	v_mul_f32_e32 v17, 0x43800000, v21
	v_mul_f32_e32 v0, 0x43800000, v23
	v_med3_f32 v17, v17, s15, v48
	v_med3_f32 v0, v0, s15, v48
	v_cvt_pk_fp8_f32 v16, v17, v0 op_sel:[0,0,1]
	v_mul_f32_e32 v0, 0x43800000, v29
	v_mul_f32_e32 v17, 0x43800000, v31
	v_med3_f32 v0, v0, s15, v48
	v_med3_f32 v19, v17, s15, v48
	v_mov_b32_e32 v17, v1
	v_cvt_pk_fp8_f32 v17, v0, v19
	v_mul_f32_e32 v18, 0x43800000, v51
	v_mul_f32_e32 v0, 0x43800000, v53
	v_med3_f32 v18, v18, s15, v48
	v_med3_f32 v0, v0, s15, v48
	global_store_dwordx2 v[54:55], v[26:27], off sc1
	v_cvt_pk_fp8_f32 v17, v18, v0 op_sel:[0,0,1]
	v_or_b32_e32 v0, s6, v35
	ds_read2_b32 v[20:21], v34 offset0:16 offset1:24
	ds_read2_b32 v[22:23], v34 offset0:49 offset1:57
	ds_read2_b32 v[26:27], v34 offset0:82 offset1:90
	ds_read2_b32 v[28:29], v34 offset0:115 offset1:123
	v_lshlrev_b32_e32 v0, 12, v0
	v_lshl_add_u64 v[18:19], v[24:25], 0, v[0:1]
	global_store_dwordx2 v[18:19], v[16:17], off sc1
	s_waitcnt lgkmcnt(3)
	v_mul_f32_e32 v0, 0x43800000, v20
	s_waitcnt lgkmcnt(2)
	v_mul_f32_e32 v16, 0x43800000, v22
	v_med3_f32 v0, v0, s15, v48
	v_med3_f32 v18, v16, s15, v48
	v_mov_b32_e32 v16, v1
	v_cvt_pk_fp8_f32 v16, v0, v18
	ds_read2_b32 v[18:19], v34 offset0:148 offset1:156
	ds_read2_b32 v[30:31], v34 offset0:181 offset1:189
	ds_read2_b32 v[50:51], v34 offset0:214 offset1:222
	s_waitcnt lgkmcnt(4)
	v_mul_f32_e32 v17, 0x43800000, v26
	s_waitcnt lgkmcnt(3)
	v_mul_f32_e32 v20, 0x43800000, v28
	v_med3_f32 v0, v17, s15, v48
	v_med3_f32 v17, v20, s15, v48
	ds_read2_b32 v[52:53], v34 offset0:247 offset1:255
	v_cvt_pk_fp8_f32 v16, v0, v17 op_sel:[0,0,1]
	s_waitcnt lgkmcnt(3)
	v_mul_f32_e32 v0, 0x43800000, v18
	s_waitcnt lgkmcnt(2)
	v_mul_f32_e32 v17, 0x43800000, v30
	v_med3_f32 v0, v0, s15, v48
	v_med3_f32 v20, v17, s15, v48
	v_mov_b32_e32 v17, v1
	v_cvt_pk_fp8_f32 v17, v0, v20
	s_waitcnt lgkmcnt(1)
	v_mul_f32_e32 v18, 0x43800000, v50
	s_waitcnt lgkmcnt(0)
	v_mul_f32_e32 v0, 0x43800000, v52
	v_med3_f32 v18, v18, s15, v48
	v_med3_f32 v0, v0, s15, v48
	v_cvt_pk_fp8_f32 v17, v18, v0 op_sel:[0,0,1]
	v_or_b32_e32 v0, s6, v36
	v_lshlrev_b32_e32 v0, 12, v0
	v_lshl_add_u64 v[54:55], v[24:25], 0, v[0:1]
	global_store_dwordx2 v[54:55], v[16:17], off sc1
	v_mul_f32_e32 v0, 0x43800000, v21
	v_mul_f32_e32 v16, 0x43800000, v23
	v_med3_f32 v0, v0, s15, v48
	v_med3_f32 v18, v16, s15, v48
	v_mov_b32_e32 v16, v1
	v_cvt_pk_fp8_f32 v16, v0, v18
	v_mul_f32_e32 v17, 0x43800000, v27
	v_mul_f32_e32 v0, 0x43800000, v29
	v_med3_f32 v17, v17, s15, v48
	v_med3_f32 v0, v0, s15, v48
	v_cvt_pk_fp8_f32 v16, v17, v0 op_sel:[0,0,1]
	v_mul_f32_e32 v0, 0x43800000, v19
	v_mul_f32_e32 v17, 0x43800000, v31
	v_med3_f32 v0, v0, s15, v48
	v_med3_f32 v19, v17, s15, v48
	v_mov_b32_e32 v17, v1
	v_cvt_pk_fp8_f32 v17, v0, v19
	v_mul_f32_e32 v18, 0x43800000, v51
	v_mul_f32_e32 v0, 0x43800000, v53
	v_med3_f32 v18, v18, s15, v48
	v_med3_f32 v0, v0, s15, v48
	v_cvt_pk_fp8_f32 v17, v18, v0 op_sel:[0,0,1]
	v_or_b32_e32 v0, s6, v37
	v_lshlrev_b32_e32 v0, 12, v0
	v_lshl_add_u64 v[18:19], v[24:25], 0, v[0:1]
	global_store_dwordx2 v[18:19], v[16:17], off sc1
	s_waitcnt lgkmcnt(0)

.LBB0_36:
	v_lshl_add_u64 v[50:51], v[16:17], 0, s[6:7]
	v_lshl_add_u64 v[52:53], v[22:23], 0, s[6:7]
	v_lshl_add_u64 v[54:55], v[30:31], 0, s[6:7]
	v_lshl_add_u64 v[56:57], v[28:29], 0, s[6:7]
	v_lshl_add_u64 v[58:59], v[26:27], 0, s[6:7]
	v_lshl_add_u64 v[60:61], v[24:25], 0, s[6:7]
	v_lshl_add_u64 v[62:63], v[20:21], 0, s[6:7]
	v_lshl_add_u64 v[64:65], v[18:19], 0, s[6:7]
	global_load_dword v50, v[50:51], off nt
	s_nop 0
	global_load_dword v51, v[52:53], off nt
	s_nop 0
	global_load_dword v52, v[54:55], off nt
	global_load_dword v53, v[56:57], off nt
	s_nop 0
	global_load_dword v54, v[58:59], off nt
	global_load_dword v55, v[60:61], off nt
	global_load_dword v56, v[62:63], off nt
	global_load_dword v57, v[64:65], off nt
	s_add_u32 s6, s6, 0xf2800
	s_addc_u32 s7, s7, 0
	v_add_u32_e32 v58, 0x400, v0
	s_cmp_eq_u32 s6, 0x3ca000
	s_waitcnt vmcnt(6)
	ds_write2_b32 v0, v50, v51 offset1:66
	s_waitcnt vmcnt(4)
	ds_write2_b32 v0, v52, v53 offset0:132 offset1:198
	s_waitcnt vmcnt(2)
	ds_write2_b32 v58, v54, v55 offset0:8 offset1:74
	s_waitcnt vmcnt(0)
	ds_write2_b32 v58, v56, v57 offset0:140 offset1:206
	v_add_u32_e32 v0, 0x840, v0
	s_cbranch_scc0 .LBB0_36
	s_waitcnt lgkmcnt(0)
	ds_read2_b32 v[20:21], v34 offset0:33 offset1:41
	ds_read2_b32 v[22:23], v34 offset1:8
	ds_read2_b32 v[24:25], v34 offset0:66 offset1:74
	ds_read2_b32 v[26:27], v34 offset0:99 offset1:107
	ds_read2_b32 v[28:29], v34 offset0:132 offset1:140
	ds_read2_b32 v[30:31], v34 offset0:165 offset1:173
	ds_read2_b32 v[50:51], v34 offset0:198 offset1:206
	ds_read2_b32 v[52:53], v34 offset0:231 offset1:239
	s_lshl_b32 s4, s10, 1
	v_or_b32_e32 v0, s23, v33
	v_lshl_add_u64 v[54:55], v[10:11], 0, s[4:5]
	v_lshlrev_b32_e32 v0, 13, v0
	s_waitcnt lgkmcnt(6)
	v_cvt_pk_f16_f32 v16, v22, v20
	s_waitcnt lgkmcnt(4)
	v_cvt_pk_f16_f32 v17, v24, v26
	s_waitcnt lgkmcnt(2)
	v_cvt_pk_f16_f32 v18, v28, v30
	s_waitcnt lgkmcnt(0)
	v_cvt_pk_f16_f32 v19, v50, v52
	v_lshl_add_u64 v[56:57], v[54:55], 0, v[0:1]
	global_store_dwordx4 v[56:57], v[16:19], off sc1
	v_or_b32_e32 v0, s23, v35
	v_lshlrev_b32_e32 v0, 13, v0
	v_cvt_pk_f16_f32 v16, v23, v21
	v_cvt_pk_f16_f32 v17, v25, v27
	v_cvt_pk_f16_f32 v18, v29, v31
	v_cvt_pk_f16_f32 v19, v51, v53
	ds_read2_b32 v[22:23], v34 offset0:49 offset1:57
	ds_read2_b32 v[24:25], v34 offset0:16 offset1:24
	ds_read2_b32 v[26:27], v34 offset0:82 offset1:90
	ds_read2_b32 v[28:29], v34 offset0:115 offset1:123
	ds_read2_b32 v[30:31], v34 offset0:148 offset1:156
	ds_read2_b32 v[50:51], v34 offset0:181 offset1:189
	ds_read2_b32 v[52:53], v34 offset0:214 offset1:222
	ds_read2_b32 v[56:57], v34 offset0:247 offset1:255
	v_lshl_add_u64 v[20:21], v[54:55], 0, v[0:1]
	v_or_b32_e32 v0, s23, v36
	v_lshlrev_b32_e32 v0, 13, v0
	global_store_dwordx4 v[20:21], v[16:19], off sc1
	v_lshl_add_u64 v[20:21], v[54:55], 0, v[0:1]
	v_or_b32_e32 v0, s23, v37
	s_waitcnt lgkmcnt(6)
	v_cvt_pk_f16_f32 v16, v24, v22
	s_waitcnt lgkmcnt(4)
	v_cvt_pk_f16_f32 v17, v26, v28
	s_waitcnt lgkmcnt(2)
	v_cvt_pk_f16_f32 v18, v30, v50
	s_waitcnt lgkmcnt(0)
	v_cvt_pk_f16_f32 v19, v52, v56
	v_lshlrev_b32_e32 v0, 13, v0
	global_store_dwordx4 v[20:21], v[16:19], off sc1
	v_lshl_add_u64 v[20:21], v[54:55], 0, v[0:1]
	s_mov_b64 s[6:7], 0
	v_cvt_pk_f16_f32 v16, v25, v23
	v_cvt_pk_f16_f32 v17, v27, v29
	v_cvt_pk_f16_f32 v18, v31, v51
	v_cvt_pk_f16_f32 v19, v53, v57
	global_store_dwordx4 v[20:21], v[16:19], off sc1
	s_waitcnt lgkmcnt(0)
.LBB0_38:
	s_and_b64 vcc, exec, s[6:7]
	s_cbranch_vccz .LBB0_40
	v_or_b32_e32 v0, s23, v33
	s_lshl_b32 s4, s10, 1
	v_lshl_add_u64 v[16:17], v[10:11], 0, s[4:5]
	v_lshlrev_b32_e32 v0, 13, v0
	v_lshl_add_u64 v[16:17], v[16:17], 0, v[0:1]
	s_mov_b32 s6, s5
	s_mov_b32 s7, s5
	s_mov_b32 s4, s5
	v_mov_b64_e32 v[22:23], s[6:7]
	v_add_co_u32_e32 v18, vcc, 0x10000, v16
	v_mov_b64_e32 v[20:21], s[4:5]
	s_nop 0
	v_addc_co_u32_e32 v19, vcc, 0, v17, vcc
	global_store_dwordx4 v[18:19], v[20:23], off sc1
	v_add_co_u32_e32 v18, vcc, 0x20000, v16
	global_store_dwordx4 v[16:17], v[20:23], off sc1
	s_nop 0
	v_addc_co_u32_e32 v19, vcc, 0, v17, vcc
	v_add_co_u32_e32 v16, vcc, 0x30000, v16
	global_store_dwordx4 v[18:19], v[20:23], off sc1
	s_nop 0
	v_addc_co_u32_e32 v17, vcc, 0, v17, vcc
	global_store_dwordx4 v[16:17], v[20:23], off sc1

.LBB0_43:
	v_lshl_add_u64 v[50:51], v[16:17], 0, s[6:7]
	v_lshl_add_u64 v[52:53], v[22:23], 0, s[6:7]
	v_lshl_add_u64 v[54:55], v[30:31], 0, s[6:7]
	v_lshl_add_u64 v[56:57], v[28:29], 0, s[6:7]
	v_lshl_add_u64 v[58:59], v[26:27], 0, s[6:7]
	v_lshl_add_u64 v[60:61], v[24:25], 0, s[6:7]
	v_lshl_add_u64 v[62:63], v[20:21], 0, s[6:7]
	v_lshl_add_u64 v[64:65], v[18:19], 0, s[6:7]
	global_load_dword v50, v[50:51], off nt
	s_nop 0
	global_load_dword v51, v[52:53], off nt
	s_nop 0
	global_load_dword v52, v[54:55], off nt
	global_load_dword v53, v[56:57], off nt
	s_nop 0
	global_load_dword v54, v[58:59], off nt
	global_load_dword v55, v[60:61], off nt
	global_load_dword v56, v[62:63], off nt
	global_load_dword v57, v[64:65], off nt
	s_add_u32 s6, s6, 0xf2800
	s_addc_u32 s7, s7, 0
	v_add_u32_e32 v58, 0x400, v0
	s_cmp_lg_u32 s6, 0x3ca000
	s_waitcnt vmcnt(6)
	ds_write2_b32 v0, v50, v51 offset1:66
	s_waitcnt vmcnt(4)
	ds_write2_b32 v0, v52, v53 offset0:132 offset1:198
	s_waitcnt vmcnt(2)
	ds_write2_b32 v58, v54, v55 offset0:8 offset1:74
	s_waitcnt vmcnt(0)
	ds_write2_b32 v58, v56, v57 offset0:140 offset1:206
	v_add_u32_e32 v0, 0x840, v0
	s_cbranch_scc1 .LBB0_43
	s_waitcnt lgkmcnt(0)
	ds_read2_b32 v[16:17], v34 offset1:8
	ds_read2_b32 v[18:19], v34 offset0:33 offset1:41
	ds_read2_b32 v[20:21], v34 offset0:66 offset1:74
	ds_read2_b32 v[22:23], v34 offset0:99 offset1:107
	v_mov_b32_e32 v26, v1
	s_waitcnt lgkmcnt(3)
	v_mul_f32_e32 v0, 0x43800000, v16
	s_waitcnt lgkmcnt(2)
	v_mul_f32_e32 v16, 0x43800000, v18
	v_med3_f32 v0, v0, s15, v48
	v_med3_f32 v16, v16, s15, v48
	v_cvt_pk_fp8_f32 v26, v0, v16
	ds_read2_b32 v[28:29], v34 offset0:132 offset1:140
	ds_read2_b32 v[30:31], v34 offset0:165 offset1:173
	ds_read2_b32 v[50:51], v34 offset0:198 offset1:206
	s_waitcnt lgkmcnt(4)
	v_mul_f32_e32 v18, 0x43800000, v20
	s_waitcnt lgkmcnt(3)
	v_mul_f32_e32 v20, 0x43800000, v22
	v_med3_f32 v0, v18, s15, v48
	v_med3_f32 v16, v20, s15, v48
	ds_read2_b32 v[52:53], v34 offset0:231 offset1:239
	v_cvt_pk_fp8_f32 v26, v0, v16 op_sel:[0,0,1]
	s_waitcnt lgkmcnt(3)
	v_mul_f32_e32 v0, 0x43800000, v28
	s_waitcnt lgkmcnt(2)
	v_mul_f32_e32 v16, 0x43800000, v30
	v_med3_f32 v0, v0, s15, v48
	v_med3_f32 v16, v16, s15, v48
	v_mov_b32_e32 v27, v1
	v_cvt_pk_fp8_f32 v27, v0, v16
	s_waitcnt lgkmcnt(1)
	v_mul_f32_e32 v18, 0x43800000, v50
	s_waitcnt lgkmcnt(0)
	v_mul_f32_e32 v0, 0x43800000, v52
	v_med3_f32 v16, v18, s15, v48
	v_med3_f32 v0, v0, s15, v48
	s_mov_b32 s11, s5
	v_cvt_pk_fp8_f32 v27, v16, v0 op_sel:[0,0,1]
	v_or_b32_e32 v0, s23, v33
	v_lshl_add_u64 v[24:25], v[12:13], 0, s[10:11]
	v_lshlrev_b32_e32 v0, 12, v0
	v_lshl_add_u64 v[54:55], v[24:25], 0, v[0:1]
	v_mul_f32_e32 v0, 0x43800000, v17
	v_mul_f32_e32 v16, 0x43800000, v19
	v_med3_f32 v0, v0, s15, v48
	v_med3_f32 v18, v16, s15, v48
	v_mov_b32_e32 v16, v1
	v_cvt_pk_fp8_f32 v16, v0, v18
	v_mul_f32_e32 v17, 0x43800000, v21
	v_mul_f32_e32 v0, 0x43800000, v23
	v_med3_f32 v17, v17, s15, v48
	v_med3_f32 v0, v0, s15, v48
	v_cvt_pk_fp8_f32 v16, v17, v0 op_sel:[0,0,1]
	v_mul_f32_e32 v0, 0x43800000, v29
	v_mul_f32_e32 v17, 0x43800000, v31
	v_med3_f32 v0, v0, s15, v48
	v_med3_f32 v19, v17, s15, v48
	v_mov_b32_e32 v17, v1
	v_cvt_pk_fp8_f32 v17, v0, v19
	v_mul_f32_e32 v18, 0x43800000, v51
	v_mul_f32_e32 v0, 0x43800000, v53
	v_med3_f32 v18, v18, s15, v48
	v_med3_f32 v0, v0, s15, v48
	global_store_dwordx2 v[54:55], v[26:27], off sc1
	v_cvt_pk_fp8_f32 v17, v18, v0 op_sel:[0,0,1]
	v_or_b32_e32 v0, s23, v35
	ds_read2_b32 v[20:21], v34 offset0:16 offset1:24
	ds_read2_b32 v[22:23], v34 offset0:49 offset1:57
	ds_read2_b32 v[26:27], v34 offset0:82 offset1:90
	ds_read2_b32 v[28:29], v34 offset0:115 offset1:123
	v_lshlrev_b32_e32 v0, 12, v0
	v_lshl_add_u64 v[18:19], v[24:25], 0, v[0:1]
	global_store_dwordx2 v[18:19], v[16:17], off sc1
	s_waitcnt lgkmcnt(3)
	v_mul_f32_e32 v0, 0x43800000, v20
	s_waitcnt lgkmcnt(2)
	v_mul_f32_e32 v16, 0x43800000, v22
	v_med3_f32 v0, v0, s15, v48
	v_med3_f32 v18, v16, s15, v48
	v_mov_b32_e32 v16, v1
	v_cvt_pk_fp8_f32 v16, v0, v18
	ds_read2_b32 v[18:19], v34 offset0:148 offset1:156
	ds_read2_b32 v[30:31], v34 offset0:181 offset1:189
	ds_read2_b32 v[50:51], v34 offset0:214 offset1:222
	s_waitcnt lgkmcnt(4)
	v_mul_f32_e32 v17, 0x43800000, v26
	s_waitcnt lgkmcnt(3)
	v_mul_f32_e32 v20, 0x43800000, v28
	v_med3_f32 v0, v17, s15, v48
	v_med3_f32 v17, v20, s15, v48
	ds_read2_b32 v[52:53], v34 offset0:247 offset1:255
	v_cvt_pk_fp8_f32 v16, v0, v17 op_sel:[0,0,1]
	s_waitcnt lgkmcnt(3)
	v_mul_f32_e32 v0, 0x43800000, v18
	s_waitcnt lgkmcnt(2)
	v_mul_f32_e32 v17, 0x43800000, v30
	v_med3_f32 v0, v0, s15, v48
	v_med3_f32 v20, v17, s15, v48
	v_mov_b32_e32 v17, v1
	v_cvt_pk_fp8_f32 v17, v0, v20
	s_waitcnt lgkmcnt(1)
	v_mul_f32_e32 v18, 0x43800000, v50
	s_waitcnt lgkmcnt(0)
	v_mul_f32_e32 v0, 0x43800000, v52
	v_med3_f32 v18, v18, s15, v48
	v_med3_f32 v0, v0, s15, v48
	v_cvt_pk_fp8_f32 v17, v18, v0 op_sel:[0,0,1]
	v_or_b32_e32 v0, s23, v36
	v_lshlrev_b32_e32 v0, 12, v0
	v_lshl_add_u64 v[54:55], v[24:25], 0, v[0:1]
	global_store_dwordx2 v[54:55], v[16:17], off sc1
	v_mul_f32_e32 v0, 0x43800000, v21
	v_mul_f32_e32 v16, 0x43800000, v23
	v_med3_f32 v0, v0, s15, v48
	v_med3_f32 v18, v16, s15, v48
	v_mov_b32_e32 v16, v1
	v_cvt_pk_fp8_f32 v16, v0, v18
	v_mul_f32_e32 v17, 0x43800000, v27
	v_mul_f32_e32 v0, 0x43800000, v29
	v_med3_f32 v17, v17, s15, v48
	v_med3_f32 v0, v0, s15, v48
	v_cvt_pk_fp8_f32 v16, v17, v0 op_sel:[0,0,1]
	v_mul_f32_e32 v0, 0x43800000, v19
	v_mul_f32_e32 v17, 0x43800000, v31
	v_med3_f32 v0, v0, s15, v48
	v_med3_f32 v19, v17, s15, v48
	v_mov_b32_e32 v17, v1
	v_cvt_pk_fp8_f32 v17, v0, v19
	v_mul_f32_e32 v18, 0x43800000, v51
	v_mul_f32_e32 v0, 0x43800000, v53
	v_med3_f32 v18, v18, s15, v48
	v_med3_f32 v0, v0, s15, v48
	v_cvt_pk_fp8_f32 v17, v18, v0 op_sel:[0,0,1]
	v_or_b32_e32 v0, s23, v37
	v_lshlrev_b32_e32 v0, 12, v0
	v_lshl_add_u64 v[18:19], v[24:25], 0, v[0:1]
	global_store_dwordx2 v[18:19], v[16:17], off sc1
	s_waitcnt lgkmcnt(0)

.LBB0_48:
	v_lshl_add_u64 v[28:29], v[18:19], 0, s[6:7]
	v_add_co_u32_e32 v30, vcc, s14, v28
	global_load_dwordx2 v[78:79], v[28:29], off nt
	s_nop 0
	v_addc_co_u32_e32 v31, vcc, 0, v29, vcc
	v_add_co_u32_e32 v50, vcc, s17, v28
	v_mov_b32_e32 v0, s10
	s_nop 0
	v_addc_co_u32_e32 v51, vcc, 0, v29, vcc
	v_add_co_u32_e32 v52, vcc, s18, v28
	s_add_u32 s6, s6, 0x60000
	s_nop 0
	v_addc_co_u32_e32 v53, vcc, 0, v29, vcc
	v_add_co_u32_e32 v54, vcc, s16, v28
	s_addc_u32 s7, s7, 0
	s_nop 0
	v_addc_co_u32_e32 v55, vcc, 0, v29, vcc
	v_add_co_u32_e32 v56, vcc, s19, v28
	s_add_i32 s10, s10, 32
	s_nop 0
	v_addc_co_u32_e32 v57, vcc, 0, v29, vcc
	v_add_co_u32_e32 v58, vcc, s20, v28
	s_cmp_eq_u32 s6, 0xc00000
	s_nop 0
	v_addc_co_u32_e32 v59, vcc, 0, v29, vcc
	v_add_co_u32_e32 v28, vcc, s21, v28
	s_nop 1
	v_addc_co_u32_e32 v29, vcc, 0, v29, vcc
	global_load_dwordx2 v[80:81], v[30:31], off nt
	global_load_dwordx2 v[82:83], v[50:51], off nt
	global_load_dwordx2 v[84:85], v[52:53], off nt
	global_load_dwordx2 v[86:87], v[54:55], off nt
	global_load_dwordx2 v[88:89], v[56:57], off nt
	global_load_dwordx2 v[90:91], v[58:59], off nt
	global_load_dwordx2 v[92:93], v[28:29], off nt
	ds_read_b128 v[28:31], v0
	ds_read_b128 v[50:53], v0 offset:16
	ds_read_b128 v[54:57], v0 offset:16384
	ds_read_b128 v[58:61], v0 offset:16400
	ds_read_b128 v[62:65], v0 offset:32768
	ds_read_b128 v[66:69], v0 offset:32784
	ds_read_b128 v[70:73], v0 offset:49152
	ds_read_b128 v[74:77], v0 offset:49168
	s_waitcnt lgkmcnt(7)
	v_mov_b32_e32 v0, v31
	s_waitcnt lgkmcnt(5)
	v_mov_b32_e32 v94, v57
	s_waitcnt lgkmcnt(3)
	v_mov_b32_e32 v96, v65
	s_waitcnt lgkmcnt(1)
	v_mov_b32_e32 v98, v73
	v_mov_b32_e32 v100, v53
	v_mov_b32_e32 v102, v61
	v_mov_b32_e32 v104, v69
	s_waitcnt lgkmcnt(0)
	v_mov_b32_e32 v106, v77
	s_waitcnt vmcnt(7)
	v_pk_fma_f32 v[24:25], v[78:79], v[28:29], v[24:25] op_sel_hi:[1,0,1]
	v_pk_fma_f32 v[26:27], v[78:79], v[54:55], v[26:27] op_sel_hi:[1,0,1]
	v_pk_fma_f32 v[22:23], v[78:79], v[62:63], v[22:23] op_sel_hi:[1,0,1]
	v_pk_fma_f32 v[20:21], v[78:79], v[70:71], v[20:21] op_sel_hi:[1,0,1]
	s_waitcnt vmcnt(6)
	v_pk_fma_f32 v[24:25], v[80:81], v[28:29], v[24:25] op_sel:[0,1,0]
	v_pk_fma_f32 v[26:27], v[80:81], v[54:55], v[26:27] op_sel:[0,1,0]
	v_pk_fma_f32 v[22:23], v[80:81], v[62:63], v[22:23] op_sel:[0,1,0]
	v_pk_fma_f32 v[20:21], v[80:81], v[70:71], v[20:21] op_sel:[0,1,0]
	s_waitcnt vmcnt(5)
	v_pk_fma_f32 v[24:25], v[82:83], v[30:31], v[24:25] op_sel_hi:[1,0,1]
	v_pk_fma_f32 v[26:27], v[82:83], v[56:57], v[26:27] op_sel_hi:[1,0,1]
	v_pk_fma_f32 v[22:23], v[82:83], v[64:65], v[22:23] op_sel_hi:[1,0,1]
	v_pk_fma_f32 v[20:21], v[82:83], v[72:73], v[20:21] op_sel_hi:[1,0,1]
	s_waitcnt vmcnt(4)
	v_pk_fma_f32 v[24:25], v[84:85], v[0:1], v[24:25] op_sel_hi:[1,0,1]
	v_pk_fma_f32 v[26:27], v[84:85], v[94:95], v[26:27] op_sel_hi:[1,0,1]
	v_pk_fma_f32 v[22:23], v[84:85], v[96:97], v[22:23] op_sel_hi:[1,0,1]
	v_pk_fma_f32 v[20:21], v[84:85], v[98:99], v[20:21] op_sel_hi:[1,0,1]
	s_waitcnt vmcnt(3)
	v_pk_fma_f32 v[24:25], v[86:87], v[50:51], v[24:25] op_sel_hi:[1,0,1]
	v_pk_fma_f32 v[26:27], v[86:87], v[58:59], v[26:27] op_sel_hi:[1,0,1]
	v_pk_fma_f32 v[22:23], v[86:87], v[66:67], v[22:23] op_sel_hi:[1,0,1]
	v_pk_fma_f32 v[20:21], v[86:87], v[74:75], v[20:21] op_sel_hi:[1,0,1]
	s_waitcnt vmcnt(2)
	v_pk_fma_f32 v[24:25], v[88:89], v[50:51], v[24:25] op_sel:[0,1,0]
	v_pk_fma_f32 v[26:27], v[88:89], v[58:59], v[26:27] op_sel:[0,1,0]
	v_pk_fma_f32 v[22:23], v[88:89], v[66:67], v[22:23] op_sel:[0,1,0]
	v_pk_fma_f32 v[20:21], v[88:89], v[74:75], v[20:21] op_sel:[0,1,0]
	s_waitcnt vmcnt(1)
	v_pk_fma_f32 v[24:25], v[90:91], v[52:53], v[24:25] op_sel_hi:[1,0,1]
	v_pk_fma_f32 v[26:27], v[90:91], v[60:61], v[26:27] op_sel_hi:[1,0,1]
	v_pk_fma_f32 v[22:23], v[90:91], v[68:69], v[22:23] op_sel_hi:[1,0,1]
	v_pk_fma_f32 v[20:21], v[90:91], v[76:77], v[20:21] op_sel_hi:[1,0,1]
	s_waitcnt vmcnt(0)
	v_pk_fma_f32 v[24:25], v[92:93], v[100:101], v[24:25] op_sel_hi:[1,0,1]
	v_pk_fma_f32 v[26:27], v[92:93], v[102:103], v[26:27] op_sel_hi:[1,0,1]
	v_pk_fma_f32 v[22:23], v[92:93], v[104:105], v[22:23] op_sel_hi:[1,0,1]
	v_pk_fma_f32 v[20:21], v[92:93], v[106:107], v[20:21] op_sel_hi:[1,0,1]
	s_cbranch_scc0 .LBB0_48
	v_lshl_add_u64 v[16:17], v[16:17], 2, s[8:9]
	v_mad_i64_i32 v[16:17], s[6:7], s4, v49, v[16:17]
	v_add_co_u32_e32 v18, vcc, 0xc000, v16
	global_store_dwordx2 v[16:17], v[24:25], off sc1
	s_nop 0
	v_addc_co_u32_e32 v19, vcc, 0, v17, vcc
	global_store_dwordx2 v[18:19], v[26:27], off sc1
	v_add_co_u32_e32 v18, vcc, 0x18000, v16
	s_nop 1
	v_addc_co_u32_e32 v19, vcc, 0, v17, vcc
	v_add_co_u32_e32 v16, vcc, 0x24000, v16
	global_store_dwordx2 v[18:19], v[22:23], off sc1
	s_nop 0
	v_addc_co_u32_e32 v17, vcc, 0, v17, vcc
	global_store_dwordx2 v[16:17], v[20:21], off sc1
	s_branch .LBB0_22

.LBB0_116:
	s_add_i32 s0, s16, s11
	s_ashr_i32 s1, s0, 31
	s_lshl_b64 s[18:19], s[0:1], 14
	ds_read_b128 v[4:7], v36
	ds_read_b128 v[0:3], v36 offset:1024
	ds_read_b128 v[12:15], v36 offset:16384
	ds_read_b128 v[8:11], v36 offset:17408
	ds_read_b128 v[16:19], v36 offset:2048
	ds_read_b128 v[20:23], v36 offset:3072
	ds_read_b128 v[56:59], v36 offset:18432
	ds_read_b128 v[60:63], v36 offset:19456
	s_lshl_b64 s[20:21], s[0:1], 12
	s_nop 0
	s_lshl_b64 s[0:1], s[0:1], 13
	s_nop 0
	v_lshl_add_u64 v[34:35], v[26:27], 0, s[0:1]
	s_nop 0
	s_nop 0
	s_nop 0
	s_nop 0
	s_nop 0
	s_nop 0
	v_add_co_u32_e32 v32, vcc, s6, v34
	v_mov_b32_e32 v40, 0
	s_nop 0
	v_addc_co_u32_e32 v33, vcc, 0, v35, vcc
	v_mov_b32_e32 v41, 0
	v_mov_b32_e32 v43, 0
	v_mov_b32_e32 v45, 0
	v_lshl_add_u64 v[30:31], v[28:29], 0, s[20:21]
	v_mov_b32_e32 v42, 0
	v_mov_b32_e32 v44, 0
	v_mov_b32_e32 v47, 0
	v_mov_b32_e32 v49, 0
	v_mov_b32_e32 v46, 0
	v_mov_b32_e32 v48, 0
	v_mov_b32_e32 v51, 0
	v_mov_b32_e32 v53, 0
	v_mov_b32_e32 v50, 0
	v_mov_b32_e32 v52, 0
	v_mov_b32_e32 v54, 0
	v_mov_b32_e32 v55, 0
	s_add_i32 s11, s11, 8
	s_add_i32 s23, s16, s11
	s_cmp_lt_i32 s11, s3
	v_mov_b32_e32 v162, s23
	v_mov_b32_e32 v163, 0
	v_lshlrev_b64 v[162:163], 14, v[162:163]
	v_lshl_add_u64 v[160:161], v[162:163], 0, v[24:25]
	v_lshl_add_u64 v[164:165], v[160:161], 0, s[26:27]
	v_lshl_add_u64 v[166:167], v[160:161], 0, s[30:31]
	v_lshl_add_u64 v[168:169], v[160:161], 0, s[34:35]
	s_waitcnt vmcnt(15)
	v_mul_f32_e32 v128, v65, v65
	v_mul_f32_e32 v129, v67, v67
	s_waitcnt vmcnt(14)
	v_mul_f32_e32 v130, v69, v69
	v_mul_f32_e32 v131, v71, v71
	s_waitcnt vmcnt(13)
	v_mul_f32_e32 v132, v73, v73
	v_mul_f32_e32 v133, v75, v75
	v_fmac_f32_e32 v128, v64, v64
	v_fmac_f32_e32 v129, v66, v66
	v_fmac_f32_e32 v130, v68, v68
	v_fmac_f32_e32 v131, v70, v70
	s_waitcnt vmcnt(12)
	v_mul_f32_e32 v134, v77, v77
	v_mul_f32_e32 v135, v79, v79
	v_fmac_f32_e32 v132, v72, v72
	v_fmac_f32_e32 v133, v74, v74
	v_add_f32_e32 v128, v128, v129
	v_add_f32_e32 v129, v130, v131
	v_fmac_f32_e32 v134, v76, v76
	v_fmac_f32_e32 v135, v78, v78
	s_waitcnt vmcnt(11)
	v_mul_f32_e32 v136, v81, v81
	v_mul_f32_e32 v137, v83, v83
	v_add_f32_e32 v130, v132, v133
	v_add_f32_e32 v128, v128, v129
	s_waitcnt vmcnt(10)
	v_mul_f32_e32 v138, v85, v85
	v_mul_f32_e32 v139, v87, v87
	v_add_f32_e32 v131, v134, v135
	v_fmac_f32_e32 v136, v80, v80
	v_fmac_f32_e32 v137, v82, v82
	v_add_f32_e32 v128, v128, v130
	s_waitcnt vmcnt(9)
	v_mul_f32_e32 v140, v89, v89
	v_mul_f32_e32 v141, v91, v91
	v_fmac_f32_e32 v138, v84, v84
	v_fmac_f32_e32 v139, v86, v86
	v_add_f32_e32 v129, v136, v137
	v_add_f32_e32 v128, v128, v131
	s_waitcnt vmcnt(8)
	v_mul_f32_e32 v142, v93, v93
	v_mul_f32_e32 v143, v95, v95
	v_fmac_f32_e32 v140, v88, v88
	v_fmac_f32_e32 v141, v90, v90
	v_add_f32_e32 v132, v138, v139
	v_add_f32_e32 v128, v128, v129
	s_waitcnt vmcnt(7)
	v_mul_f32_e32 v144, v97, v97
	v_mul_f32_e32 v145, v99, v99
	v_fmac_f32_e32 v142, v92, v92
	v_fmac_f32_e32 v143, v94, v94
	v_add_f32_e32 v133, v140, v141
	v_add_f32_e32 v128, v128, v132
	s_waitcnt vmcnt(6)
	v_mul_f32_e32 v146, v101, v101
	v_mul_f32_e32 v147, v103, v103
	v_fmac_f32_e32 v144, v96, v96
	v_fmac_f32_e32 v145, v98, v98
	v_add_f32_e32 v134, v142, v143
	v_add_f32_e32 v128, v128, v133
	s_waitcnt vmcnt(5)
	v_mul_f32_e32 v148, v105, v105
	v_mul_f32_e32 v149, v107, v107
	v_fmac_f32_e32 v146, v100, v100
	v_fmac_f32_e32 v147, v102, v102
	v_add_f32_e32 v135, v144, v145
	v_add_f32_e32 v128, v128, v134
	s_waitcnt vmcnt(4)
	v_mul_f32_e32 v150, v109, v109
	v_mul_f32_e32 v151, v111, v111
	v_fmac_f32_e32 v148, v104, v104
	v_fmac_f32_e32 v149, v106, v106
	v_add_f32_e32 v136, v146, v147
	v_add_f32_e32 v128, v128, v135
	s_waitcnt vmcnt(3)
	v_mul_f32_e32 v152, v113, v113
	v_mul_f32_e32 v153, v115, v115
	v_fmac_f32_e32 v150, v108, v108
	v_fmac_f32_e32 v151, v110, v110
	v_add_f32_e32 v137, v148, v149
	v_add_f32_e32 v128, v128, v136
	s_waitcnt vmcnt(2)
	v_mul_f32_e32 v154, v117, v117
	v_mul_f32_e32 v155, v119, v119
	v_fmac_f32_e32 v152, v112, v112
	v_fmac_f32_e32 v153, v114, v114
	v_add_f32_e32 v138, v150, v151
	v_add_f32_e32 v128, v128, v137
	s_waitcnt vmcnt(1)
	v_mul_f32_e32 v156, v121, v121
	v_mul_f32_e32 v157, v123, v123
	v_fmac_f32_e32 v154, v116, v116
	v_fmac_f32_e32 v155, v118, v118
	v_add_f32_e32 v139, v152, v153
	v_add_f32_e32 v128, v128, v138
	s_waitcnt vmcnt(0)
	v_mul_f32_e32 v158, v125, v125
	v_mul_f32_e32 v159, v127, v127
	v_fmac_f32_e32 v156, v120, v120
	v_fmac_f32_e32 v157, v122, v122
	v_add_f32_e32 v140, v154, v155
	v_add_f32_e32 v128, v128, v139
	v_fmac_f32_e32 v158, v124, v124
	v_fmac_f32_e32 v159, v126, v126
	v_add_f32_e32 v141, v156, v157
	v_add_f32_e32 v128, v128, v140
	v_add_f32_e32 v142, v158, v159
	v_add_f32_e32 v128, v128, v141
	v_add_f32_e32 v128, v128, v142
	s_nop 1
	v_add_f32_dpp v128, v128, v128 quad_perm:[1,0,3,2] row_mask:0xf bank_mask:0xf bound_ctrl:1
	s_nop 1
	v_add_f32_dpp v128, v128, v128 quad_perm:[2,3,0,1] row_mask:0xf bank_mask:0xf bound_ctrl:1
	s_nop 1
	v_add_f32_dpp v128, v128, v128 row_half_mirror row_mask:0xf bank_mask:0xf bound_ctrl:1
	s_nop 1
	v_add_f32_dpp v128, v128, v128 row_mirror row_mask:0xf bank_mask:0xf bound_ctrl:1
	v_mov_b32_e32 v129, v128
	s_nop 1
	v_permlane16_swap_b32_e32 v128, v129
	v_add_f32_e32 v128, v128, v129
	v_mov_b32_e32 v129, v128
	s_nop 1
	v_permlane32_swap_b32_e32 v128, v129
	v_add_f32_e32 v128, v128, v129
	v_fmamk_f32 v128, v128, 0x39800000, v37
	v_mul_f32_e32 v129, 0x4f800000, v128
	v_cmp_gt_f32_e32 vcc, s9, v128
	s_nop 1
	v_cndmask_b32_e32 v128, v128, v129, vcc
	v_sqrt_f32_e32 v129, v128
	s_nop 0
	v_add_u32_e32 v130, -1, v129
	v_add_u32_e32 v131, 1, v129
	v_fma_f32 v132, -v130, v129, v128
	v_fma_f32 v133, -v131, v129, v128
	v_cmp_ge_f32_e64 s[0:1], 0, v132
	s_nop 1
	v_cndmask_b32_e64 v129, v129, v130, s[0:1]
	v_cmp_lt_f32_e64 s[0:1], 0, v133
	s_nop 1
	v_cndmask_b32_e64 v129, v129, v131, s[0:1]
	v_mul_f32_e32 v130, 0x37800000, v129
	v_cndmask_b32_e32 v129, v129, v130, vcc
	v_cmp_class_f32_e32 vcc, v128, v38
	s_nop 1
	v_cndmask_b32_e32 v128, v129, v128, vcc
	v_div_scale_f32 v129, s[0:1], v128, v128, 1.0
	v_rcp_f32_e32 v131, v129
	v_div_scale_f32 v130, vcc, 1.0, v128, 1.0
	v_fma_f32 v132, -v129, v131, 1.0
	v_fmac_f32_e32 v131, v132, v131
	v_mul_f32_e32 v132, v130, v131
	v_fma_f32 v133, -v129, v132, v130
	v_fmac_f32_e32 v132, v133, v131
	v_fma_f32 v129, -v129, v132, v130
	v_div_fmas_f32 v129, v129, v131, v132
	v_div_fixup_f32 v128, v129, v128, 1.0
	v_pk_mul_f32 v[64:65], v[128:129], v[64:65] op_sel_hi:[0,1]
	v_pk_mul_f32 v[66:67], v[128:129], v[66:67] op_sel_hi:[0,1]
	v_pk_mul_f32 v[68:69], v[128:129], v[68:69] op_sel_hi:[0,1]
	v_pk_mul_f32 v[70:71], v[128:129], v[70:71] op_sel_hi:[0,1]
	v_pk_mul_f32 v[72:73], v[128:129], v[72:73] op_sel_hi:[0,1]
	v_pk_mul_f32 v[74:75], v[128:129], v[74:75] op_sel_hi:[0,1]
	s_waitcnt lgkmcnt(5)
	v_pk_fma_f32 v[6:7], v[14:15], v[66:67], v[6:7]
	v_pk_fma_f32 v[4:5], v[12:13], v[64:65], v[4:5]
	s_waitcnt lgkmcnt(4)
	v_pk_fma_f32 v[2:3], v[10:11], v[70:71], v[2:3]
	v_pk_fma_f32 v[0:1], v[8:9], v[68:69], v[0:1]
	s_waitcnt lgkmcnt(1)
	v_pk_fma_f32 v[8:9], v[58:59], v[74:75], v[18:19]
	v_pk_fma_f32 v[10:11], v[56:57], v[72:73], v[16:17]
	v_cvt_pk_f16_f32 v16, v4, v5
	v_cvt_pk_f16_f32 v17, v6, v7
	v_mul_f32_e32 v18, 0x41800000, v4
	v_mul_f32_e32 v19, 0x41800000, v5
	v_pk_mul_f32 v[76:77], v[128:129], v[76:77] op_sel_hi:[0,1]
	global_store_dwordx2 v[34:35], v[16:17], off sc1
	v_med3_f32 v16, v18, s10, v39
	v_med3_f32 v17, v19, s10, v39
	s_waitcnt lgkmcnt(0)
	v_pk_fma_f32 v[14:15], v[60:61], v[76:77], v[20:21]
	v_mul_f32_e32 v20, 0x41800000, v0
	v_mul_f32_e32 v21, 0x41800000, v1
	v_cvt_pk_fp8_f32 v40, v16, v17
	v_pk_mul_f32 v[78:79], v[128:129], v[78:79] op_sel_hi:[0,1]
	v_med3_f32 v18, v20, s10, v39
	v_med3_f32 v19, v21, s10, v39
	v_pk_fma_f32 v[12:13], v[62:63], v[78:79], v[22:23]
	v_mul_f32_e32 v6, 0x41800000, v6
	v_mul_f32_e32 v7, 0x41800000, v7
	v_cvt_pk_f16_f32 v4, v0, v1
	v_cvt_pk_f16_f32 v5, v2, v3
	v_mul_f32_e32 v22, 0x41800000, v2
	v_cvt_pk_f16_f32 v0, v10, v11
	v_mul_f32_e32 v10, 0x41800000, v10
	v_mul_f32_e32 v11, 0x41800000, v11
	v_cvt_pk_f16_f32 v2, v14, v15
	v_mul_f32_e32 v14, 0x41800000, v14
	v_mul_f32_e32 v15, 0x41800000, v15
	v_cvt_pk_fp8_f32 v41, v18, v19
	v_med3_f32 v6, v6, s10, v39
	v_med3_f32 v7, v7, s10, v39
	v_med3_f32 v10, v10, s10, v39
	v_med3_f32 v11, v11, s10, v39
	v_med3_f32 v14, v14, s10, v39
	v_med3_f32 v15, v15, s10, v39
	v_mul_f32_e32 v23, 0x41800000, v3
	v_cvt_pk_fp8_f32 v43, v10, v11
	v_cvt_pk_fp8_f32 v45, v14, v15
	v_cvt_pk_fp8_f32 v40, v6, v7 op_sel:[0,0,1]
	v_med3_f32 v20, v22, s10, v39
	v_med3_f32 v21, v23, s10, v39
	v_cvt_pk_f16_f32 v1, v8, v9
	v_mul_f32_e32 v8, 0x41800000, v8
	v_mul_f32_e32 v9, 0x41800000, v9
	v_cvt_pk_f16_f32 v3, v12, v13
	v_mul_f32_e32 v12, 0x41800000, v12
	v_mul_f32_e32 v13, 0x41800000, v13
	v_cvt_pk_fp8_f32 v41, v20, v21 op_sel:[0,0,1]
	v_med3_f32 v8, v8, s10, v39
	v_med3_f32 v9, v9, s10, v39
	v_med3_f32 v12, v12, s10, v39
	v_med3_f32 v13, v13, s10, v39
	v_cvt_pk_fp8_f32 v43, v8, v9 op_sel:[0,0,1]
	v_cvt_pk_fp8_f32 v45, v12, v13 op_sel:[0,0,1]
	global_store_dword v[30:31], v40, off sc1
	global_store_dwordx2 v[34:35], v[4:5], off offset:512 sc1
	global_store_dword v[30:31], v41, off offset:256 sc1
	global_store_dwordx2 v[34:35], v[0:1], off offset:1024 sc1
	global_store_dword v[30:31], v43, off offset:512 sc1
	global_store_dwordx2 v[34:35], v[2:3], off offset:1536 sc1
	global_store_dword v[30:31], v45, off offset:768 sc1
	s_cbranch_scc0 .Lp1_nopf0
	global_load_dwordx4 v[64:67], v[160:161], off nt
	global_load_dwordx4 v[68:71], v[160:161], off offset:1024 nt
	global_load_dwordx4 v[72:75], v[160:161], off offset:2048 nt
	global_load_dwordx4 v[76:79], v[160:161], off offset:3072 nt
.Lp1_nopf0:
	ds_read_b128 v[0:3], v36 offset:4096
	ds_read_b128 v[4:7], v36 offset:5120
	ds_read_b128 v[8:11], v36 offset:20480
	ds_read_b128 v[12:15], v36 offset:21504
	ds_read_b128 v[16:19], v36 offset:6144
	ds_read_b128 v[20:23], v36 offset:7168
	ds_read_b128 v[56:59], v36 offset:22528
	ds_read_b128 v[60:63], v36 offset:23552
	v_pk_mul_f32 v[80:81], v[128:129], v[80:81] op_sel_hi:[0,1]
	v_pk_mul_f32 v[82:83], v[128:129], v[82:83] op_sel_hi:[0,1]
	v_pk_mul_f32 v[88:89], v[128:129], v[88:89] op_sel_hi:[0,1]
	v_pk_mul_f32 v[90:91], v[128:129], v[90:91] op_sel_hi:[0,1]
	s_waitcnt lgkmcnt(5)
	v_pk_fma_f32 v[2:3], v[10:11], v[82:83], v[2:3]
	v_pk_fma_f32 v[0:1], v[8:9], v[80:81], v[0:1]
	v_pk_mul_f32 v[84:85], v[128:129], v[84:85] op_sel_hi:[0,1]
	s_waitcnt lgkmcnt(1)
	v_pk_fma_f32 v[8:9], v[58:59], v[90:91], v[18:19]
	v_pk_fma_f32 v[10:11], v[56:57], v[88:89], v[16:17]
	v_cvt_pk_f16_f32 v16, v0, v1
	v_cvt_pk_f16_f32 v17, v2, v3
	v_mul_f32_e32 v18, 0x41800000, v0
	v_mul_f32_e32 v19, 0x41800000, v1
	v_pk_mul_f32 v[86:87], v[128:129], v[86:87] op_sel_hi:[0,1]
	v_pk_mul_f32 v[92:93], v[128:129], v[92:93] op_sel_hi:[0,1]
	v_pk_mul_f32 v[94:95], v[128:129], v[94:95] op_sel_hi:[0,1]
	v_pk_fma_f32 v[4:5], v[12:13], v[84:85], v[4:5]
	global_store_dwordx2 v[34:35], v[16:17], off offset:2048 sc1
	v_med3_f32 v16, v18, s10, v39
	v_med3_f32 v17, v19, s10, v39
	v_pk_fma_f32 v[6:7], v[14:15], v[86:87], v[6:7]
	s_waitcnt lgkmcnt(0)
	v_pk_fma_f32 v[12:13], v[62:63], v[94:95], v[22:23]
	v_pk_fma_f32 v[14:15], v[60:61], v[92:93], v[20:21]
	v_mul_f32_e32 v20, 0x41800000, v2
	v_mul_f32_e32 v21, 0x41800000, v3
	v_mul_f32_e32 v22, 0x41800000, v4
	v_mul_f32_e32 v23, 0x41800000, v5
	v_cvt_pk_fp8_f32 v42, v16, v17
	v_med3_f32 v18, v20, s10, v39
	v_med3_f32 v19, v21, s10, v39
	v_med3_f32 v20, v22, s10, v39
	v_med3_f32 v21, v23, s10, v39
	v_cvt_pk_f16_f32 v0, v4, v5
	v_cvt_pk_f16_f32 v2, v10, v11
	v_mul_f32_e32 v10, 0x41800000, v10
	v_mul_f32_e32 v11, 0x41800000, v11
	v_cvt_pk_f16_f32 v4, v14, v15
	v_mul_f32_e32 v14, 0x41800000, v14
	v_mul_f32_e32 v15, 0x41800000, v15
	v_cvt_pk_fp8_f32 v44, v20, v21
	v_med3_f32 v10, v10, s10, v39
	v_med3_f32 v11, v11, s10, v39
	v_med3_f32 v14, v14, s10, v39
	v_med3_f32 v15, v15, s10, v39
	v_cvt_pk_f16_f32 v1, v6, v7
	v_mul_f32_e32 v6, 0x41800000, v6
	v_mul_f32_e32 v7, 0x41800000, v7
	v_cvt_pk_fp8_f32 v47, v10, v11
	v_cvt_pk_fp8_f32 v49, v14, v15
	v_cvt_pk_fp8_f32 v42, v18, v19 op_sel:[0,0,1]
	v_med3_f32 v6, v6, s10, v39
	v_med3_f32 v7, v7, s10, v39
	v_cvt_pk_f16_f32 v3, v8, v9
	v_mul_f32_e32 v8, 0x41800000, v8
	v_mul_f32_e32 v9, 0x41800000, v9
	v_cvt_pk_f16_f32 v5, v12, v13
	v_mul_f32_e32 v12, 0x41800000, v12
	v_mul_f32_e32 v13, 0x41800000, v13
	v_cvt_pk_fp8_f32 v44, v6, v7 op_sel:[0,0,1]
	v_med3_f32 v8, v8, s10, v39
	v_med3_f32 v9, v9, s10, v39
	v_med3_f32 v12, v12, s10, v39
	v_med3_f32 v13, v13, s10, v39
	v_cvt_pk_fp8_f32 v47, v8, v9 op_sel:[0,0,1]
	v_cvt_pk_fp8_f32 v49, v12, v13 op_sel:[0,0,1]
	global_store_dword v[30:31], v42, off offset:1024 sc1
	global_store_dwordx2 v[34:35], v[0:1], off offset:2560 sc1
	global_store_dword v[30:31], v44, off offset:1280 sc1
	global_store_dwordx2 v[34:35], v[2:3], off offset:3072 sc1
	global_store_dword v[30:31], v47, off offset:1536 sc1
	global_store_dwordx2 v[34:35], v[4:5], off offset:3584 sc1
	global_store_dword v[30:31], v49, off offset:1792 sc1
	s_cbranch_scc0 .Lp1_nopf1
	global_load_dwordx4 v[80:83], v[164:165], off nt
	global_load_dwordx4 v[84:87], v[164:165], off offset:1024 nt
	global_load_dwordx4 v[88:91], v[164:165], off offset:2048 nt
	global_load_dwordx4 v[92:95], v[164:165], off offset:3072 nt
.Lp1_nopf1:
	ds_read_b128 v[0:3], v36 offset:8192
	ds_read_b128 v[4:7], v36 offset:9216
	ds_read_b128 v[8:11], v36 offset:24576
	ds_read_b128 v[12:15], v36 offset:25600
	ds_read_b128 v[16:19], v36 offset:10240
	ds_read_b128 v[20:23], v36 offset:11264
	ds_read_b128 v[40:43], v36 offset:26624
	ds_read_b128 v[56:59], v36 offset:27648
	v_pk_mul_f32 v[96:97], v[128:129], v[96:97] op_sel_hi:[0,1]
	v_pk_mul_f32 v[98:99], v[128:129], v[98:99] op_sel_hi:[0,1]
	v_pk_mul_f32 v[104:105], v[128:129], v[104:105] op_sel_hi:[0,1]
	v_pk_mul_f32 v[106:107], v[128:129], v[106:107] op_sel_hi:[0,1]
	s_waitcnt lgkmcnt(5)
	v_pk_fma_f32 v[2:3], v[10:11], v[98:99], v[2:3]
	v_pk_fma_f32 v[0:1], v[8:9], v[96:97], v[0:1]
	v_pk_mul_f32 v[100:101], v[128:129], v[100:101] op_sel_hi:[0,1]
	s_waitcnt lgkmcnt(1)
	v_pk_fma_f32 v[8:9], v[42:43], v[106:107], v[18:19]
	v_pk_fma_f32 v[10:11], v[40:41], v[104:105], v[16:17]
	v_cvt_pk_f16_f32 v16, v0, v1
	v_cvt_pk_f16_f32 v17, v2, v3
	v_mul_f32_e32 v18, 0x41800000, v0
	v_mul_f32_e32 v19, 0x41800000, v1
	v_pk_mul_f32 v[102:103], v[128:129], v[102:103] op_sel_hi:[0,1]
	v_pk_mul_f32 v[108:109], v[128:129], v[108:109] op_sel_hi:[0,1]
	v_pk_mul_f32 v[110:111], v[128:129], v[110:111] op_sel_hi:[0,1]
	v_pk_fma_f32 v[4:5], v[12:13], v[100:101], v[4:5]
	global_store_dwordx2 v[32:33], v[16:17], off sc1
	v_med3_f32 v16, v18, s10, v39
	v_med3_f32 v17, v19, s10, v39
	v_pk_fma_f32 v[6:7], v[14:15], v[102:103], v[6:7]
	s_waitcnt lgkmcnt(0)
	v_pk_fma_f32 v[12:13], v[58:59], v[110:111], v[22:23]
	v_pk_fma_f32 v[14:15], v[56:57], v[108:109], v[20:21]
	v_mul_f32_e32 v20, 0x41800000, v2
	v_mul_f32_e32 v21, 0x41800000, v3
	v_mul_f32_e32 v22, 0x41800000, v4
	v_mul_f32_e32 v23, 0x41800000, v5
	v_cvt_pk_fp8_f32 v46, v16, v17
	v_med3_f32 v18, v20, s10, v39
	v_med3_f32 v19, v21, s10, v39
	v_med3_f32 v20, v22, s10, v39
	v_med3_f32 v21, v23, s10, v39
	v_cvt_pk_f16_f32 v0, v4, v5
	v_cvt_pk_f16_f32 v2, v10, v11
	v_mul_f32_e32 v10, 0x41800000, v10
	v_mul_f32_e32 v11, 0x41800000, v11
	v_cvt_pk_f16_f32 v4, v14, v15
	v_mul_f32_e32 v14, 0x41800000, v14
	v_mul_f32_e32 v15, 0x41800000, v15
	v_cvt_pk_fp8_f32 v48, v20, v21
	v_med3_f32 v10, v10, s10, v39
	v_med3_f32 v11, v11, s10, v39
	v_med3_f32 v14, v14, s10, v39
	v_med3_f32 v15, v15, s10, v39
	v_cvt_pk_f16_f32 v1, v6, v7
	v_mul_f32_e32 v6, 0x41800000, v6
	v_mul_f32_e32 v7, 0x41800000, v7
	v_cvt_pk_fp8_f32 v51, v10, v11
	v_cvt_pk_fp8_f32 v53, v14, v15
	v_cvt_pk_fp8_f32 v46, v18, v19 op_sel:[0,0,1]
	v_med3_f32 v6, v6, s10, v39
	v_med3_f32 v7, v7, s10, v39
	v_cvt_pk_f16_f32 v3, v8, v9
	v_mul_f32_e32 v8, 0x41800000, v8
	v_mul_f32_e32 v9, 0x41800000, v9
	v_cvt_pk_f16_f32 v5, v12, v13
	v_mul_f32_e32 v12, 0x41800000, v12
	v_mul_f32_e32 v13, 0x41800000, v13
	v_cvt_pk_fp8_f32 v48, v6, v7 op_sel:[0,0,1]
	v_med3_f32 v8, v8, s10, v39
	v_med3_f32 v9, v9, s10, v39
	v_med3_f32 v12, v12, s10, v39
	v_med3_f32 v13, v13, s10, v39
	v_cvt_pk_fp8_f32 v51, v8, v9 op_sel:[0,0,1]
	v_cvt_pk_fp8_f32 v53, v12, v13 op_sel:[0,0,1]
	global_store_dword v[30:31], v46, off offset:2048 sc1
	global_store_dwordx2 v[32:33], v[0:1], off offset:512 sc1
	global_store_dword v[30:31], v48, off offset:2304 sc1
	global_store_dwordx2 v[32:33], v[2:3], off offset:1024 sc1
	global_store_dword v[30:31], v51, off offset:2560 sc1
	global_store_dwordx2 v[32:33], v[4:5], off offset:1536 sc1
	global_store_dword v[30:31], v53, off offset:2816 sc1
	s_cbranch_scc0 .Lp1_nopf2
	global_load_dwordx4 v[96:99], v[166:167], off nt
	global_load_dwordx4 v[100:103], v[166:167], off offset:1024 nt
	global_load_dwordx4 v[104:107], v[166:167], off offset:2048 nt
	global_load_dwordx4 v[108:111], v[166:167], off offset:3072 nt
.Lp1_nopf2:
	ds_read_b128 v[0:3], v36 offset:12288
	ds_read_b128 v[4:7], v36 offset:13312
	ds_read_b128 v[8:11], v36 offset:28672
	ds_read_b128 v[12:15], v36 offset:29696
	ds_read_b128 v[16:19], v36 offset:14336
	ds_read_b128 v[20:23], v36 offset:15360
	ds_read_b128 v[40:43], v36 offset:30720
	ds_read_b128 v[44:47], v36 offset:31744
	v_pk_mul_f32 v[112:113], v[128:129], v[112:113] op_sel_hi:[0,1]
	v_pk_mul_f32 v[114:115], v[128:129], v[114:115] op_sel_hi:[0,1]
	v_pk_mul_f32 v[120:121], v[128:129], v[120:121] op_sel_hi:[0,1]
	v_pk_mul_f32 v[122:123], v[128:129], v[122:123] op_sel_hi:[0,1]
	s_waitcnt lgkmcnt(5)
	v_pk_fma_f32 v[2:3], v[10:11], v[114:115], v[2:3]
	v_pk_fma_f32 v[0:1], v[8:9], v[112:113], v[0:1]
	v_pk_mul_f32 v[116:117], v[128:129], v[116:117] op_sel_hi:[0,1]
	s_waitcnt lgkmcnt(1)
	v_pk_fma_f32 v[8:9], v[42:43], v[122:123], v[18:19]
	v_pk_fma_f32 v[10:11], v[40:41], v[120:121], v[16:17]
	v_cvt_pk_f16_f32 v16, v0, v1
	v_cvt_pk_f16_f32 v17, v2, v3
	v_mul_f32_e32 v18, 0x41800000, v0
	v_mul_f32_e32 v19, 0x41800000, v1
	v_pk_mul_f32 v[118:119], v[128:129], v[118:119] op_sel_hi:[0,1]
	v_pk_mul_f32 v[124:125], v[128:129], v[124:125] op_sel_hi:[0,1]
	v_pk_mul_f32 v[126:127], v[128:129], v[126:127] op_sel_hi:[0,1]
	v_pk_fma_f32 v[4:5], v[12:13], v[116:117], v[4:5]
	global_store_dwordx2 v[32:33], v[16:17], off offset:2048 sc1
	v_med3_f32 v16, v18, s10, v39
	v_med3_f32 v17, v19, s10, v39
	v_pk_fma_f32 v[6:7], v[14:15], v[118:119], v[6:7]
	s_waitcnt lgkmcnt(0)
	v_pk_fma_f32 v[12:13], v[46:47], v[126:127], v[22:23]
	v_pk_fma_f32 v[14:15], v[44:45], v[124:125], v[20:21]
	v_mul_f32_e32 v20, 0x41800000, v2
	v_mul_f32_e32 v21, 0x41800000, v3
	v_mul_f32_e32 v22, 0x41800000, v4
	v_mul_f32_e32 v23, 0x41800000, v5
	v_cvt_pk_fp8_f32 v50, v16, v17
	v_med3_f32 v18, v20, s10, v39
	v_med3_f32 v19, v21, s10, v39
	v_med3_f32 v20, v22, s10, v39
	v_med3_f32 v21, v23, s10, v39
	v_cvt_pk_f16_f32 v0, v4, v5
	v_cvt_pk_f16_f32 v2, v10, v11
	v_mul_f32_e32 v10, 0x41800000, v10
	v_mul_f32_e32 v11, 0x41800000, v11
	v_cvt_pk_f16_f32 v4, v14, v15
	v_mul_f32_e32 v14, 0x41800000, v14
	v_mul_f32_e32 v15, 0x41800000, v15
	v_cvt_pk_fp8_f32 v52, v20, v21
	v_med3_f32 v10, v10, s10, v39
	v_med3_f32 v11, v11, s10, v39
	v_med3_f32 v14, v14, s10, v39
	v_med3_f32 v15, v15, s10, v39
	v_cvt_pk_f16_f32 v1, v6, v7
	v_mul_f32_e32 v6, 0x41800000, v6
	v_mul_f32_e32 v7, 0x41800000, v7
	v_cvt_pk_fp8_f32 v54, v10, v11
	v_cvt_pk_fp8_f32 v55, v14, v15
	v_cvt_pk_fp8_f32 v50, v18, v19 op_sel:[0,0,1]
	v_med3_f32 v6, v6, s10, v39
	v_med3_f32 v7, v7, s10, v39
	v_cvt_pk_f16_f32 v3, v8, v9
	v_mul_f32_e32 v8, 0x41800000, v8
	v_mul_f32_e32 v9, 0x41800000, v9
	v_cvt_pk_f16_f32 v5, v12, v13
	v_mul_f32_e32 v12, 0x41800000, v12
	v_mul_f32_e32 v13, 0x41800000, v13
	v_cvt_pk_fp8_f32 v52, v6, v7 op_sel:[0,0,1]
	v_med3_f32 v8, v8, s10, v39
	v_med3_f32 v9, v9, s10, v39
	v_med3_f32 v12, v12, s10, v39
	v_med3_f32 v13, v13, s10, v39
	v_cvt_pk_fp8_f32 v54, v8, v9 op_sel:[0,0,1]
	v_cvt_pk_fp8_f32 v55, v12, v13 op_sel:[0,0,1]
	global_store_dword v[30:31], v50, off offset:3072 sc1
	global_store_dwordx2 v[32:33], v[0:1], off offset:2560 sc1
	global_store_dword v[30:31], v52, off offset:3328 sc1
	global_store_dwordx2 v[32:33], v[2:3], off offset:3072 sc1
	global_store_dword v[30:31], v54, off offset:3584 sc1
	global_store_dwordx2 v[32:33], v[4:5], off offset:3584 sc1
	global_store_dword v[30:31], v55, off offset:3840 sc1
	s_cbranch_scc0 .Lp1_nopf3
	global_load_dwordx4 v[112:115], v[168:169], off nt
	global_load_dwordx4 v[116:119], v[168:169], off offset:1024 nt
	global_load_dwordx4 v[120:123], v[168:169], off offset:2048 nt
	global_load_dwordx4 v[124:127], v[168:169], off offset:3072 nt
